# grid barrier: XCD leader bumps the per-XCD generation before its own acquire invalidate (inv moved after the atomic)
# speedup vs baseline: 1.0085x; 1.0032x over previous
.LBB0_192:
	s_or_b64 exec, exec, s[6:7]
	v_mov_b32_e32 v0, 0x2000
	v_mov_b32_e32 v1, 1
	s_waitcnt vmcnt(0)
	global_atomic_add v0, v1, s[4:5] offset:1024
	buffer_inv sc1
	s_waitcnt vmcnt(0)

.LBB0_269:
	s_or_b64 exec, exec, s[8:9]
	v_readlane_b32 s4, v253, 38
	v_readlane_b32 s5, v253, 39
	s_waitcnt vmcnt(0)
	s_nop 3
	global_atomic_add v1, v181, s[4:5]
	buffer_inv sc1
	s_waitcnt vmcnt(0)
